# MLA attention: conflict-free K tile LDS layout (pitch 320B + 32B skew), on top of the diff-loop changes
# speedup vs baseline: 1.0035x; 1.0025x over previous
.LBB0_159:
	s_mul_hi_i32 s1, s6, s80
	s_mul_i32 s0, s6, s80
	s_lshl_b64 s[6:7], s[0:1], 11
	s_add_u32 s6, s89, s6
	s_addc_u32 s7, s90, s7
	s_lshl_b32 s8, s12, 8
	s_add_u32 s30, s6, s8
	s_addc_u32 s31, s7, 0
	s_lshl_b64 s[0:1], s[0:1], 6
	s_add_u32 s74, s85, s0
	s_movk_i32 s0, 0x300
	v_add_u32_e32 v8, 0xfffffe00, v90
	v_cmp_gt_i32_e32 vcc, s0, v90
	s_addc_u32 s75, s86, s1
	s_nop 0
	v_cndmask_b32_e32 v8, v8, v90, vcc
	v_mul_hi_i32 v9, v8, s34
	v_lshrrev_b32_e32 v10, 31, v9
	v_ashrrev_i32_e32 v9, 1, v9
	v_add_u32_e32 v154, v9, v10
	v_mul_lo_u32 v9, v154, 12
	v_sub_u32_e32 v30, v8, v9
	v_cmp_gt_i32_e64 s[6:7], 8, v30
	v_cmp_lt_i32_e32 vcc, 7, v30
	v_ashrrev_i32_e32 v155, 31, v154
	v_lshlrev_b32_e32 v84, 3, v30
	s_and_saveexec_b64 s[0:1], vcc
	s_xor_b64 s[8:9], exec, s[0:1]
	v_lshlrev_b64 v[8:9], 6, v[154:155]
	v_lshl_add_u64 v[8:9], s[74:75], 0, v[8:9]
	v_mov_b32_e32 v85, v193
	v_lshl_add_u64 v[8:9], v[84:85], 1, v[8:9]
	v_lshl_add_u64 v[8:9], v[8:9], 0, s[58:59]
	s_or_saveexec_b64 s[8:9], s[8:9]
	v_ashrrev_i32_e32 v93, 31, v84
	s_xor_b64 exec, exec, s[8:9]
	v_lshlrev_b64 v[8:9], 11, v[154:155]
	v_lshl_add_u64 v[8:9], s[30:31], 0, v[8:9]
	v_mov_b32_e32 v85, v93
	v_lshl_add_u64 v[8:9], v[84:85], 1, v[8:9]
	s_or_b64 exec, exec, s[8:9]
	global_load_dwordx4 v[8:11], v[8:9], off
	s_movk_i32 s0, 0x100
	v_add_u32_e32 v28, 0x200, v90
	v_cmp_gt_i32_e64 s[8:9], s0, v90
	s_nop 1
	v_cndmask_b32_e64 v28, v90, v28, s[8:9]
	v_mul_hi_i32 v29, v28, s34
	v_lshrrev_b32_e32 v31, 31, v29
	v_ashrrev_i32_e32 v29, 1, v29
	v_add_u32_e32 v156, v29, v31
	v_mul_lo_u32 v29, v156, 12
	v_sub_u32_e32 v31, v28, v29
	v_cmp_gt_i32_e64 s[8:9], 8, v31
	v_cmp_lt_i32_e64 s[10:11], 7, v31
	v_ashrrev_i32_e32 v157, 31, v156
	v_lshlrev_b32_e32 v86, 3, v31
	s_and_saveexec_b64 s[0:1], s[10:11]
	s_xor_b64 s[26:27], exec, s[0:1]
	v_lshlrev_b64 v[28:29], 6, v[156:157]
	v_lshl_add_u64 v[28:29], s[74:75], 0, v[28:29]
	v_mov_b32_e32 v87, v193
	v_lshl_add_u64 v[28:29], v[86:87], 1, v[28:29]
	v_lshl_add_u64 v[28:29], v[28:29], 0, s[58:59]
	s_or_saveexec_b64 s[26:27], s[26:27]
	v_ashrrev_i32_e32 v94, 31, v86
	s_xor_b64 exec, exec, s[26:27]
	v_lshlrev_b64 v[28:29], 11, v[156:157]
	v_lshl_add_u64 v[28:29], s[30:31], 0, v[28:29]
	v_mov_b32_e32 v87, v94
	v_lshl_add_u64 v[28:29], v[86:87], 1, v[28:29]
	s_or_b64 exec, exec, s[26:27]
	global_load_dwordx4 v[34:37], v[28:29], off
	v_mul_u32_u24_e32 v151, 0x140, v154
	v_and_b32_e32 v255, 16, v154
	v_lshl_add_u32 v151, v255, 1, v151
	v_add_u32_e32 v28, 0, v151
	v_lshlrev_b32_e32 v155, 4, v30
	v_add_u32_e32 v33, v28, v155
	v_mul_u32_u24_e32 v157, 0x140, v156
	v_and_b32_e32 v255, 16, v156
	v_lshl_add_u32 v157, v255, 1, v157
	s_waitcnt vmcnt(1)
	ds_write_b128 v33, v[8:11] offset:28672
	v_add_u32_e32 v8, 0, v157
	v_lshlrev_b32_e32 v170, 4, v31
	v_add_u32_e32 v32, v8, v170
	v_add_u32_e32 v8, 64, v154
	v_ashrrev_i32_e32 v9, 31, v8
	s_waitcnt vmcnt(0)
	ds_write_b128 v32, v[34:37] offset:28672
	s_and_saveexec_b64 s[0:1], vcc
	s_xor_b64 s[26:27], exec, s[0:1]
	v_lshlrev_b64 v[8:9], 6, v[8:9]
	v_lshl_add_u64 v[8:9], s[74:75], 0, v[8:9]
	v_mov_b32_e32 v85, v193
	v_lshl_add_u64 v[8:9], v[84:85], 1, v[8:9]
	v_lshl_add_u64 v[10:11], v[8:9], 0, s[58:59]
	s_andn2_saveexec_b64 s[26:27], s[26:27]
	v_lshlrev_b64 v[8:9], 11, v[8:9]
	v_lshl_add_u64 v[8:9], s[30:31], 0, v[8:9]
	v_mov_b32_e32 v85, v93
	v_lshl_add_u64 v[10:11], v[84:85], 1, v[8:9]
	s_or_b64 exec, exec, s[26:27]
	global_load_dwordx4 v[8:11], v[10:11], off
	v_add_u32_e32 v30, 64, v156
	v_ashrrev_i32_e32 v31, 31, v30
	s_and_saveexec_b64 s[0:1], s[10:11]
	s_xor_b64 s[26:27], exec, s[0:1]
	v_lshlrev_b64 v[28:29], 6, v[30:31]
	v_lshl_add_u64 v[28:29], s[74:75], 0, v[28:29]
	v_mov_b32_e32 v87, v193
	v_lshl_add_u64 v[28:29], v[86:87], 1, v[28:29]
	v_lshl_add_u64 v[28:29], v[28:29], 0, s[58:59]
	s_andn2_saveexec_b64 s[26:27], s[26:27]
	v_lshlrev_b64 v[28:29], 11, v[30:31]
	v_lshl_add_u64 v[28:29], s[30:31], 0, v[28:29]
	v_mov_b32_e32 v87, v94
	v_lshl_add_u64 v[28:29], v[86:87], 1, v[28:29]
	s_or_b64 exec, exec, s[26:27]
	v_ashrrev_i32_e32 v34, 31, v90
	v_lshrrev_b32_e32 v34, 29, v34
	v_add_u32_e32 v34, v90, v34
	v_ashrrev_i32_e32 v158, 3, v34
	v_and_b32_e32 v34, -8, v34
	v_sub_u32_e32 v38, v90, v34
	v_ashrrev_i32_e32 v159, 31, v158
	v_lshlrev_b64 v[34:35], 11, v[158:159]
	v_lshlrev_b32_e32 v88, 3, v38
	v_lshl_add_u64 v[34:35], s[30:31], 0, v[34:35]
	v_ashrrev_i32_e32 v89, 31, v88
	global_load_dwordx4 v[28:31], v[28:29], off
	v_lshl_add_u64 v[34:35], v[88:89], 1, v[34:35]
	global_load_dwordx4 v[34:37], v[34:35], off offset:128
	s_waitcnt vmcnt(2)
	ds_write_b128 v33, v[8:11]
	v_lshrrev_b32_e32 v10, 2, v158
	v_bfe_u32 v9, v158, 1, 1
	v_and_b32_e32 v10, 2, v10
	v_lshrrev_b32_e32 v33, 1, v38
	v_lshlrev_b32_e32 v171, 7, v158
	v_lshlrev_b32_e32 v38, 4, v38
	v_bitop3_b32 v9, v9, v33, v10 bitop3:0x36
	v_add_u32_e32 v11, 0, v171
	v_and_b32_e32 v172, 16, v38
	v_lshlrev_b32_e32 v173, 5, v9
	v_add_u32_e32 v8, 0x80, v154
	v_add3_u32 v9, v11, v173, v172
	s_waitcnt vmcnt(1)
	ds_write_b128 v32, v[28:31]
	s_waitcnt vmcnt(0)
	ds_write_b128 v9, v[34:37] offset:20480
	v_ashrrev_i32_e32 v9, 31, v8
	s_and_saveexec_b64 s[0:1], vcc
	s_xor_b64 s[26:27], exec, s[0:1]
	v_lshlrev_b64 v[8:9], 6, v[8:9]
	v_lshl_add_u64 v[8:9], s[74:75], 0, v[8:9]
	v_mov_b32_e32 v85, v193
	v_lshl_add_u64 v[8:9], v[84:85], 1, v[8:9]
	v_lshl_add_u64 v[10:11], v[8:9], 0, s[58:59]
	s_andn2_saveexec_b64 s[26:27], s[26:27]
	v_lshlrev_b64 v[8:9], 11, v[8:9]
	v_lshl_add_u64 v[8:9], s[30:31], 0, v[8:9]
	v_mov_b32_e32 v85, v93
	v_lshl_add_u64 v[10:11], v[84:85], 1, v[8:9]
	s_or_b64 exec, exec, s[26:27]
	global_load_dwordx4 v[8:11], v[10:11], off
	v_add_u32_e32 v30, 0x80, v156
	v_ashrrev_i32_e32 v31, 31, v30
	s_and_saveexec_b64 s[0:1], s[10:11]
	s_xor_b64 s[10:11], exec, s[0:1]
	v_lshlrev_b64 v[28:29], 6, v[30:31]
	v_lshl_add_u64 v[28:29], s[74:75], 0, v[28:29]
	v_mov_b32_e32 v87, v193
	v_lshl_add_u64 v[28:29], v[86:87], 1, v[28:29]
	v_lshl_add_u64 v[28:29], v[28:29], 0, s[58:59]
	s_andn2_saveexec_b64 s[10:11], s[10:11]
	v_lshlrev_b64 v[28:29], 11, v[30:31]
	v_lshl_add_u64 v[28:29], s[30:31], 0, v[28:29]
	v_mov_b32_e32 v87, v94
	v_lshl_add_u64 v[28:29], v[86:87], 1, v[28:29]
	s_or_b64 exec, exec, s[10:11]
	v_lshlrev_b32_e32 v30, 16, v12
	v_and_b32_e32 v31, 0xffff0000, v12
	v_pk_mul_f32 v[30:31], v[30:31], s[56:57] op_sel_hi:[1,0]
	v_lshlrev_b64 v[32:33], 11, v[158:159]
	v_cvt_pk_bf16_f32 v12, v30, v31
	v_lshlrev_b32_e32 v30, 16, v13
	v_and_b32_e32 v31, 0xffff0000, v13
	v_pk_mul_f32 v[30:31], v[30:31], s[56:57] op_sel_hi:[1,0]
	v_lshl_add_u64 v[32:33], s[30:31], 0, v[32:33]
	v_cvt_pk_bf16_f32 v13, v30, v31
	v_lshlrev_b32_e32 v30, 16, v14
	v_and_b32_e32 v31, 0xffff0000, v14
	v_pk_mul_f32 v[30:31], v[30:31], s[56:57] op_sel_hi:[1,0]
	v_lshrrev_b32_e32 v85, 2, v92
	v_cvt_pk_bf16_f32 v14, v30, v31
	v_lshlrev_b32_e32 v30, 16, v15
	v_and_b32_e32 v31, 0xffff0000, v15
	v_pk_mul_f32 v[30:31], v[30:31], s[56:57] op_sel_hi:[1,0]
	v_lshl_add_u64 v[32:33], v[88:89], 1, v[32:33]
	v_cvt_pk_bf16_f32 v15, v30, v31
	v_lshlrev_b32_e32 v30, 16, v16
	v_and_b32_e32 v31, 0xffff0000, v16
	v_pk_mul_f32 v[30:31], v[30:31], s[56:57] op_sel_hi:[1,0]
	v_and_b32_e32 v36, 3, v90
	v_cvt_pk_bf16_f32 v16, v30, v31
	v_lshlrev_b32_e32 v30, 16, v17
	v_and_b32_e32 v31, 0xffff0000, v17
	v_pk_mul_f32 v[30:31], v[30:31], s[56:57] op_sel_hi:[1,0]
	v_add_co_u32_e32 v32, vcc, s33, v32
	v_cvt_pk_bf16_f32 v17, v30, v31
	v_lshlrev_b32_e32 v30, 16, v18
	v_and_b32_e32 v31, 0xffff0000, v18
	v_pk_mul_f32 v[30:31], v[30:31], s[56:57] op_sel_hi:[1,0]
	v_lshl_or_b32 v36, v85, 3, v36
	v_cvt_pk_bf16_f32 v18, v30, v31
	v_lshlrev_b32_e32 v30, 16, v19
	v_and_b32_e32 v31, 0xffff0000, v19
	v_pk_mul_f32 v[30:31], v[30:31], s[56:57] op_sel_hi:[1,0]
	v_addc_co_u32_e32 v33, vcc, 0, v33, vcc
	v_cvt_pk_bf16_f32 v19, v30, v31
	v_lshlrev_b32_e32 v30, 16, v20
	v_and_b32_e32 v31, 0xffff0000, v20
	v_pk_mul_f32 v[30:31], v[30:31], s[56:57] op_sel_hi:[1,0]
	v_mul_u32_u24_e32 v159, 0x140, v36
	v_and_b32_e32 v255, 16, v36
	v_lshl_add_u32 v159, v255, 1, v159
	v_cvt_pk_bf16_f32 v20, v30, v31
	v_lshlrev_b32_e32 v30, 16, v21
	v_and_b32_e32 v31, 0xffff0000, v21
	v_pk_mul_f32 v[30:31], v[30:31], s[56:57] op_sel_hi:[1,0]
	global_load_dwordx4 v[32:35], v[32:33], off offset:128
	v_cvt_pk_bf16_f32 v21, v30, v31
	v_lshlrev_b32_e32 v30, 16, v22
	v_and_b32_e32 v31, 0xffff0000, v22
	v_pk_mul_f32 v[30:31], v[30:31], s[56:57] op_sel_hi:[1,0]
	v_add3_u32 v80, 0, v192, v159
	v_cvt_pk_bf16_f32 v22, v30, v31
	v_lshlrev_b32_e32 v30, 16, v23
	v_and_b32_e32 v31, 0xffff0000, v23
	v_pk_mul_f32 v[30:31], v[30:31], s[56:57] op_sel_hi:[1,0]
	s_cmp_eq_u64 exec, 0
	v_cvt_pk_bf16_f32 v23, v30, v31
	v_lshlrev_b32_e32 v30, 16, v24
	v_and_b32_e32 v31, 0xffff0000, v24
	v_pk_mul_f32 v[30:31], v[30:31], s[56:57] op_sel_hi:[1,0]
	s_nop 0
	v_cvt_pk_bf16_f32 v24, v30, v31
	v_lshlrev_b32_e32 v30, 16, v25
	v_and_b32_e32 v31, 0xffff0000, v25
	v_pk_mul_f32 v[30:31], v[30:31], s[56:57] op_sel_hi:[1,0]
	s_nop 0
	v_cvt_pk_bf16_f32 v25, v30, v31
	v_lshlrev_b32_e32 v30, 16, v26
	v_and_b32_e32 v31, 0xffff0000, v26
	v_pk_mul_f32 v[30:31], v[30:31], s[56:57] op_sel_hi:[1,0]
	s_nop 0
	v_cvt_pk_bf16_f32 v26, v30, v31
	v_lshlrev_b32_e32 v30, 16, v27
	v_and_b32_e32 v31, 0xffff0000, v27
	v_pk_mul_f32 v[30:31], v[30:31], s[56:57] op_sel_hi:[1,0]
	s_nop 0
	v_cvt_pk_bf16_f32 v27, v30, v31
	global_load_dwordx4 v[28:31], v[28:29], off
	s_waitcnt lgkmcnt(0)
	s_barrier
	ds_read_b128 v[36:39], v80 offset:28672
	ds_read_b128 v[68:71], v80 offset:28736
	s_waitcnt lgkmcnt(1)
	v_mfma_f32_16x16x32_bf16 v[40:43], v[36:39], v[12:15], 0
	ds_read_b128 v[44:47], v80 offset:29952
	ds_read_b128 v[52:55], v80 offset:38912
	ds_read_b128 v[60:63], v80 offset:40192
	v_mfma_f32_16x16x32_bf16 v[36:39], v[36:39], v[20:23], 0
	s_waitcnt lgkmcnt(3)
	v_mfma_f32_16x16x32_bf16 v[40:43], v[68:71], v[16:19], v[40:43]
	v_mfma_f32_16x16x32_bf16 v[36:39], v[68:71], v[24:27], v[36:39]
	ds_read_b128 v[68:71], v80 offset:30016
	s_waitcnt lgkmcnt(3)
	v_mfma_f32_16x16x32_bf16 v[48:51], v[44:47], v[12:15], 0
	v_mfma_f32_16x16x32_bf16 v[44:47], v[44:47], v[20:23], 0
	s_waitcnt lgkmcnt(0)
	v_mfma_f32_16x16x32_bf16 v[48:51], v[68:71], v[16:19], v[48:51]
	v_mfma_f32_16x16x32_bf16 v[44:47], v[68:71], v[24:27], v[44:47]
	ds_read_b128 v[68:71], v80 offset:38976
	v_mfma_f32_16x16x32_bf16 v[56:59], v[52:55], v[12:15], 0
	v_mfma_f32_16x16x32_bf16 v[52:55], v[52:55], v[20:23], 0
	s_waitcnt lgkmcnt(0)
	v_mfma_f32_16x16x32_bf16 v[72:75], v[68:71], v[16:19], v[56:59]
	v_mfma_f32_16x16x32_bf16 v[68:71], v[68:71], v[24:27], v[52:55]
	s_nop 4
	ds_read_b128 v[52:55], v80 offset:40256
	v_mfma_f32_16x16x32_bf16 v[64:67], v[60:63], v[12:15], 0
	v_mfma_f32_16x16x32_bf16 v[60:63], v[60:63], v[20:23], 0
	s_waitcnt lgkmcnt(0)
	v_mfma_f32_16x16x32_bf16 v[76:79], v[52:55], v[16:19], v[64:67]
	v_mfma_f32_16x16x32_bf16 v[96:99], v[52:55], v[24:27], v[60:63]
	ds_read_b128 v[52:55], v80 offset:28800
	s_waitcnt lgkmcnt(0)
	v_mfma_f32_16x16x32_bf16 v[64:67], v[52:55], v[4:7], v[36:39]
	s_nop 2
	ds_read_b128 v[36:39], v80 offset:30080
	v_mfma_f32_16x16x32_bf16 v[56:59], v[52:55], v[0:3], v[40:43]
	s_waitcnt lgkmcnt(0)
	v_mfma_f32_16x16x32_bf16 v[52:55], v[36:39], v[0:3], v[48:51]
	v_mfma_f32_16x16x32_bf16 v[60:63], v[36:39], v[4:7], v[44:47]
	ds_read_b128 v[36:39], v80 offset:39040
	s_waitcnt lgkmcnt(0)
	v_mfma_f32_16x16x32_bf16 v[72:75], v[36:39], v[0:3], v[72:75]
	v_mfma_f32_16x16x32_bf16 v[68:71], v[36:39], v[4:7], v[68:71]
	ds_read_b128 v[36:39], v80 offset:40320
	s_waitcnt lgkmcnt(0)
	v_mfma_f32_16x16x32_bf16 v[80:83], v[36:39], v[0:3], v[76:79]
	v_mfma_f32_16x16x32_bf16 v[76:79], v[36:39], v[4:7], v[96:99]
	v_max_f32_e32 v36, v57, v57
	v_max_f32_e32 v37, v56, v56
	v_max_f32_e32 v36, v37, v36
	v_max3_f32 v36, v36, v58, v59
	v_max3_f32 v36, v36, v52, v53
	v_max3_f32 v36, v36, v54, v55
	v_max3_f32 v36, v36, v72, v73
	v_max3_f32 v36, v36, v74, v75
	v_max3_f32 v36, v36, v80, v81
	v_max3_f32 v36, v36, v82, v83
	v_mov_b32_e32 v37, v36
	s_nop 1
	v_permlane16_swap_b32_e32 v36, v37
	v_max_f32_e32 v37, v37, v37
	v_max_f32_e32 v36, v36, v36
	v_max_f32_e32 v36, v36, v37
	v_mov_b32_e32 v37, v36
	s_nop 1
	v_permlane32_swap_b32_e32 v36, v37
	s_cbranch_scc1 .LBB0_185
	v_max_f32_e32 v36, v36, v36
	v_max_f32_e32 v37, v37, v37
	v_max_f32_e32 v36, v36, v37
	v_exp_f32_e64 v37, -v36
	v_sub_f32_e32 v59, v59, v36
	v_sub_f32_e32 v58, v58, v36
	v_sub_f32_e32 v57, v57, v36
	v_mul_f32_e32 v40, 0, v37
	v_sub_f32_e32 v56, v56, v36
	v_sub_f32_e32 v55, v55, v36
	v_sub_f32_e32 v54, v54, v36
	v_sub_f32_e32 v53, v53, v36
	v_sub_f32_e32 v52, v52, v36
	v_sub_f32_e32 v75, v75, v36
	v_sub_f32_e32 v74, v74, v36
	v_sub_f32_e32 v73, v73, v36
	v_sub_f32_e32 v72, v72, v36
	v_sub_f32_e32 v83, v83, v36
	v_sub_f32_e32 v82, v82, v36
	v_sub_f32_e32 v81, v81, v36
	v_sub_f32_e32 v80, v80, v36
	v_sub_f32_e32 v36, 0, v36
	v_mov_b32_e32 v41, v40
	v_mov_b32_e32 v42, v40
	v_mov_b32_e32 v43, v40
	v_mov_b32_e32 v37, v36
	v_mov_b32_e32 v38, v36
	v_mov_b32_e32 v39, v36
	s_branch .LBB0_186

.LBB0_190:
	s_bitcmp1_b32 s1, 0
	s_cselect_b32 s0, 0x7000, 0
	s_add_i32 s0, s0, 0
	v_add_u32_e32 v100, s0, v174
	v_add3_u32 v100, v100, v175, v176
	v_add_u32_e32 v184, v100, v177
	v_add_u32_e32 v183, v100, v178
	v_add_u32_e32 v182, v100, v179
	v_add_u32_e32 v181, v100, v180
	v_add3_u32 v185, s0, v192, v159
	ds_read_b64_tr_b16 v[112:113], v184 offset:20480
	ds_read_b64_tr_b16 v[114:115], v184 offset:20992
	ds_read_b64_tr_b16 v[108:109], v183 offset:20480
	ds_read_b64_tr_b16 v[110:111], v183 offset:20992
	ds_read_b64_tr_b16 v[104:105], v182 offset:20480
	ds_read_b64_tr_b16 v[106:107], v182 offset:20992
	ds_read_b64_tr_b16 v[100:101], v181 offset:20480
	ds_read_b64_tr_b16 v[102:103], v181 offset:20992
	ds_read_b128 v[116:119], v185
	ds_read_b128 v[186:189], v185 offset:64
	s_waitcnt lgkmcnt(1)
	v_mfma_f32_16x16x32_bf16 v[120:123], v[116:119], v[12:15], v[36:39]
	ds_read_b128 v[124:127], v185 offset:1280
	ds_read_b128 v[132:135], v185 offset:10240
	ds_read_b128 v[140:143], v185 offset:11520
	v_mfma_f32_16x16x32_bf16 v[116:119], v[116:119], v[20:23], v[48:51]
	s_andn2_b32 s0, 1, s1
	s_mulk_i32 s0, 0x7000
	s_add_i32 s0, s0, 0
	s_waitcnt lgkmcnt(3)
	v_mfma_f32_16x16x32_bf16 v[120:123], v[186:189], v[16:19], v[120:123]
	s_add_i32 s10, s1, 1
	v_mfma_f32_16x16x32_bf16 v[116:119], v[186:189], v[24:27], v[116:119]
	ds_read_b128 v[186:189], v185 offset:1344
	s_waitcnt lgkmcnt(3)
	v_mfma_f32_16x16x32_bf16 v[128:131], v[124:127], v[12:15], v[36:39]
	v_mfma_f32_16x16x32_bf16 v[124:127], v[124:127], v[20:23], v[48:51]
	s_waitcnt lgkmcnt(0)
	v_mfma_f32_16x16x32_bf16 v[128:131], v[186:189], v[16:19], v[128:131]
	v_mfma_f32_16x16x32_bf16 v[124:127], v[186:189], v[24:27], v[124:127]
	ds_read_b128 v[186:189], v185 offset:10304
	v_mfma_f32_16x16x32_bf16 v[136:139], v[132:135], v[12:15], v[36:39]
	v_mfma_f32_16x16x32_bf16 v[132:135], v[132:135], v[20:23], v[48:51]
	s_waitcnt lgkmcnt(0)
	v_mfma_f32_16x16x32_bf16 v[194:197], v[186:189], v[16:19], v[136:139]
	v_mfma_f32_16x16x32_bf16 v[186:189], v[186:189], v[24:27], v[132:135]
	s_nop 4
	ds_read_b128 v[132:135], v185 offset:11584
	v_mfma_f32_16x16x32_bf16 v[144:147], v[140:143], v[12:15], v[36:39]
	v_mfma_f32_16x16x32_bf16 v[140:143], v[140:143], v[20:23], v[48:51]
	s_waitcnt lgkmcnt(0)
	v_mfma_f32_16x16x32_bf16 v[144:147], v[132:135], v[16:19], v[144:147]
	v_mfma_f32_16x16x32_bf16 v[202:205], v[132:135], v[24:27], v[140:143]
	ds_read_b128 v[132:135], v185 offset:128
	s_waitcnt lgkmcnt(0)
	v_mfma_f32_16x16x32_bf16 v[136:139], v[132:135], v[0:3], v[120:123]
	v_mfma_f32_16x16x32_bf16 v[120:123], v[132:135], v[4:7], v[116:119]
	s_nop 2
	ds_read_b128 v[116:119], v185 offset:1408
	s_waitcnt lgkmcnt(0)
	v_mfma_f32_16x16x32_bf16 v[132:135], v[116:119], v[0:3], v[128:131]
	s_nop 2
	ds_read_b128 v[128:131], v185 offset:11648
	v_mfma_f32_16x16x32_bf16 v[116:119], v[116:119], v[4:7], v[124:127]
	s_nop 2
	ds_read_b128 v[124:127], v185 offset:10368
	v_add3_u32 v185, s0, v151, v155
	s_waitcnt vmcnt(2)
	ds_write_b128 v185, v[8:11]
	v_add3_u32 v8, s0, v157, v170
	s_waitcnt vmcnt(0)
	ds_write_b128 v8, v[28:31]
	v_add_u32_e32 v8, s0, v171
	s_add_i32 s0, s1, 3
	s_min_u32 s0, s0, s83
	v_add3_u32 v8, v8, v173, v172
	s_lshl_b32 s0, s0, 6
	ds_write_b128 v8, v[32:35] offset:20480
	v_add_u32_e32 v8, s0, v154
	v_add_u32_e32 v28, s0, v156
	s_add_i32 s0, s1, 2
	v_ashrrev_i32_e32 v9, 31, v8
	v_ashrrev_i32_e32 v29, 31, v28
	s_min_u32 s0, s0, s83
	v_lshlrev_b64 v[10:11], 11, v[8:9]
	v_lshlrev_b64 v[8:9], 6, v[8:9]
	v_lshlrev_b64 v[30:31], 11, v[28:29]
	v_lshlrev_b64 v[28:29], 6, v[28:29]
	v_lshl_add_u32 v32, s0, 6, v158
	v_lshl_add_u64 v[8:9], v[162:163], 0, v[8:9]
	v_lshl_add_u64 v[28:29], v[166:167], 0, v[28:29]
	v_ashrrev_i32_e32 v33, 31, v32
	v_lshl_add_u64 v[10:11], v[164:165], 0, v[10:11]
	v_lshl_add_u64 v[8:9], v[8:9], 0, s[58:59]
	v_lshl_add_u64 v[30:31], v[168:169], 0, v[30:31]
	v_lshl_add_u64 v[28:29], v[28:29], 0, s[58:59]
	v_lshlrev_b64 v[32:33], 11, v[32:33]
	v_cndmask_b32_e64 v9, v9, v11, s[6:7]
	v_cndmask_b32_e64 v8, v8, v10, s[6:7]
	v_cndmask_b32_e64 v29, v29, v31, s[8:9]
	v_cndmask_b32_e64 v28, v28, v30, s[8:9]
	v_lshl_add_u64 v[32:33], v[160:161], 0, v[32:33]
	global_load_dwordx4 v[8:11], v[8:9], off
	s_waitcnt lgkmcnt(3)
	v_mfma_f32_16x16x32_bf16 v[140:143], v[124:127], v[0:3], v[194:197]
	global_load_dwordx4 v[28:31], v[28:29], off
	s_cmp_ge_u32 s10, s82
	global_load_dwordx4 v[32:35], v[32:33], off offset:128
	v_mfma_f32_16x16x32_bf16 v[124:127], v[124:127], v[4:7], v[186:189]
	v_mfma_f32_16x16x32_bf16 v[144:147], v[128:131], v[0:3], v[144:147]
	v_mfma_f32_16x16x32_bf16 v[128:131], v[128:131], v[4:7], v[202:205]
	s_cbranch_scc1 .LBB0_196
	s_cmp_lg_u32 s1, 0
	s_cselect_b64 s[0:1], -1, 0
	s_and_b32 s11, s10, 3
	s_cmp_lg_u32 s11, 0
	s_cselect_b64 s[14:15], -1, 0
	s_and_b64 s[0:1], s[0:1], s[14:15]
	s_and_b64 vcc, exec, s[0:1]
	s_cbranch_vccnz .LBB0_196
	v_max_f32_e32 v185, v137, v137
	v_max_f32_e32 v186, v136, v136
	v_max_f32_e32 v185, v186, v185
	v_max3_f32 v185, v185, v138, v139
	v_max3_f32 v185, v185, v132, v133
	v_max3_f32 v185, v185, v134, v135
	v_max3_f32 v185, v185, v140, v141
	v_max3_f32 v185, v185, v142, v143
	v_max3_f32 v185, v185, v144, v145
	v_max3_f32 v185, v185, v146, v147
	v_mov_b32_e32 v186, v185
	s_nop 1
	v_permlane16_swap_b32_e32 v185, v186
	v_max_f32_e32 v186, v186, v186
	v_max_f32_e32 v185, v185, v185
	v_max_f32_e32 v185, v185, v186
	v_mov_b32_e32 v186, v185
	s_nop 1
	v_permlane32_swap_b32_e32 v185, v186
	v_max_f32_e32 v186, v186, v186
	v_max_f32_e32 v185, v185, v185
	v_max_f32_e32 v185, v185, v186
	v_cmp_lt_f32_e32 vcc, s44, v185
	s_cbranch_vccz .LBB0_194
	s_nop 0
	v_cndmask_b32_e32 v185, 0, v185, vcc
	v_exp_f32_e64 v186, -v185
	v_lshlrev_b32_e32 v188, 16, v56
	v_and_b32_e32 v189, 0xffff0000, v56
	v_sub_f32_e32 v139, v139, v185
	v_pk_mul_f32 v[188:189], v[186:187], v[188:189] op_sel_hi:[0,1]
	v_cvt_pk_bf16_f32 v56, v188, v189
	v_lshlrev_b32_e32 v188, 16, v57
	v_and_b32_e32 v189, 0xffff0000, v57
	v_pk_mul_f32 v[188:189], v[186:187], v[188:189] op_sel_hi:[0,1]
	v_cvt_pk_bf16_f32 v57, v188, v189
	v_lshlrev_b32_e32 v188, 16, v58
	v_and_b32_e32 v189, 0xffff0000, v58
	v_pk_mul_f32 v[188:189], v[186:187], v[188:189] op_sel_hi:[0,1]
	v_cvt_pk_bf16_f32 v58, v188, v189
	v_lshlrev_b32_e32 v188, 16, v59
	v_and_b32_e32 v189, 0xffff0000, v59
	v_pk_mul_f32 v[188:189], v[186:187], v[188:189] op_sel_hi:[0,1]
	v_cvt_pk_bf16_f32 v59, v188, v189
	v_lshlrev_b32_e32 v188, 16, v52
	v_and_b32_e32 v189, 0xffff0000, v52
	v_pk_mul_f32 v[188:189], v[186:187], v[188:189] op_sel_hi:[0,1]
	v_cvt_pk_bf16_f32 v52, v188, v189
	v_lshlrev_b32_e32 v188, 16, v53
	v_and_b32_e32 v189, 0xffff0000, v53
	v_pk_mul_f32 v[188:189], v[186:187], v[188:189] op_sel_hi:[0,1]
	v_cvt_pk_bf16_f32 v53, v188, v189
	v_lshlrev_b32_e32 v188, 16, v54
	v_and_b32_e32 v189, 0xffff0000, v54
	v_pk_mul_f32 v[188:189], v[186:187], v[188:189] op_sel_hi:[0,1]
	v_cvt_pk_bf16_f32 v54, v188, v189
	v_lshlrev_b32_e32 v188, 16, v55
	v_and_b32_e32 v189, 0xffff0000, v55
	v_pk_mul_f32 v[78:79], v[78:79], v[186:187] op_sel_hi:[1,0]
	v_pk_mul_f32 v[76:77], v[76:77], v[186:187] op_sel_hi:[1,0]
	v_pk_mul_f32 v[98:99], v[98:99], v[186:187] op_sel_hi:[1,0]
	v_pk_mul_f32 v[96:97], v[96:97], v[186:187] op_sel_hi:[1,0]
	v_pk_mul_f32 v[94:95], v[94:95], v[186:187] op_sel_hi:[1,0]
	v_pk_mul_f32 v[92:93], v[92:93], v[186:187] op_sel_hi:[1,0]
	v_pk_mul_f32 v[86:87], v[86:87], v[186:187] op_sel_hi:[1,0]
	v_pk_mul_f32 v[84:85], v[84:85], v[186:187] op_sel_hi:[1,0]
	v_pk_mul_f32 v[42:43], v[42:43], v[186:187] op_sel_hi:[1,0]
	v_pk_mul_f32 v[40:41], v[40:41], v[186:187] op_sel_hi:[1,0]
	v_pk_mul_f32 v[186:187], v[186:187], v[188:189] op_sel_hi:[0,1]
	v_sub_f32_e32 v138, v138, v185
	v_sub_f32_e32 v137, v137, v185
	v_sub_f32_e32 v136, v136, v185
	v_sub_f32_e32 v135, v135, v185
	v_sub_f32_e32 v134, v134, v185
	v_sub_f32_e32 v133, v133, v185
	v_sub_f32_e32 v132, v132, v185
	v_sub_f32_e32 v143, v143, v185
	v_sub_f32_e32 v142, v142, v185
	v_sub_f32_e32 v141, v141, v185
	v_sub_f32_e32 v140, v140, v185
	v_sub_f32_e32 v147, v147, v185
	v_sub_f32_e32 v146, v146, v185
	v_sub_f32_e32 v145, v145, v185
	v_sub_f32_e32 v144, v144, v185
	v_cvt_pk_bf16_f32 v55, v186, v187
	v_sub_f32_e32 v39, v39, v185
	v_sub_f32_e32 v38, v38, v185
	v_sub_f32_e32 v37, v37, v185
	v_sub_f32_e32 v36, v36, v185

.LBB0_196:
	v_mfma_f32_16x16x32_bf16 v[96:99], v[112:115], v[56:59], v[96:99]
	v_exp_f32_e32 v136, v136
	v_exp_f32_e32 v137, v137
	v_exp_f32_e32 v138, v138
	v_mfma_f32_16x16x32_bf16 v[88:91], v[112:115], v[68:71], v[88:91]
	ds_read_b64_tr_b16 v[112:113], v184 offset:24576
	ds_read_b64_tr_b16 v[114:115], v184 offset:25088
	v_exp_f32_e32 v139, v139
	v_mfma_f32_16x16x32_bf16 v[92:95], v[108:111], v[56:59], v[92:95]
	v_exp_f32_e32 v184, v133
	v_exp_f32_e32 v185, v134
	v_exp_f32_e32 v186, v135
	v_mfma_f32_16x16x32_bf16 v[80:83], v[108:111], v[68:71], v[80:83]
	ds_read_b64_tr_b16 v[108:109], v183 offset:24576
	ds_read_b64_tr_b16 v[110:111], v183 offset:25088
	v_exp_f32_e32 v183, v132
	v_mfma_f32_16x16x32_bf16 v[84:87], v[104:107], v[56:59], v[84:87]
	v_exp_f32_e32 v140, v140
	v_exp_f32_e32 v141, v141
	v_exp_f32_e32 v142, v142
	v_mfma_f32_16x16x32_bf16 v[72:75], v[104:107], v[68:71], v[72:75]
	ds_read_b64_tr_b16 v[104:105], v182 offset:24576
	ds_read_b64_tr_b16 v[106:107], v182 offset:25088
	v_exp_f32_e32 v143, v143
	s_mov_b32 s30, s28
	s_mov_b32 s31, s28
	s_mov_b32 s29, s28
	v_mov_b64_e32 v[134:135], s[30:31]
	v_mov_b64_e32 v[132:133], s[28:29]
	v_mfma_f32_16x16x32_bf16 v[40:43], v[100:103], v[56:59], v[40:43]
	v_exp_f32_e32 v144, v144
	v_exp_f32_e32 v145, v145
	v_exp_f32_e32 v146, v146
	v_mfma_f32_16x16x32_bf16 v[44:47], v[100:103], v[68:71], v[44:47]
	ds_read_b64_tr_b16 v[100:101], v181 offset:24576
	ds_read_b64_tr_b16 v[102:103], v181 offset:25088
	v_exp_f32_e32 v147, v147
	v_mfma_f32_16x16x32_bf16 v[76:79], v[132:135], v[56:59], v[76:79]
	v_mfma_f32_16x16x32_bf16 v[60:63], v[132:135], v[68:71], v[60:63]
	v_exp_f32_e32 v68, v120
	v_exp_f32_e32 v69, v121
	s_waitcnt lgkmcnt(6)
	v_mfma_f32_16x16x32_bf16 v[96:99], v[112:115], v[52:55], v[96:99]
	v_exp_f32_e32 v70, v122
	v_exp_f32_e32 v71, v123
	v_cvt_pk_bf16_f32 v56, v136, v137
	v_mfma_f32_16x16x32_bf16 v[88:91], v[112:115], v[64:67], v[88:91]
	v_cvt_pk_bf16_f32 v57, v138, v139
	v_cvt_pk_bf16_f32 v58, v183, v184
	v_cvt_pk_bf16_f32 v59, v185, v186
	s_waitcnt lgkmcnt(4)
	v_mfma_f32_16x16x32_bf16 v[92:95], v[108:111], v[52:55], v[92:95]
	v_exp_f32_e32 v112, v116
	v_exp_f32_e32 v113, v117
	v_exp_f32_e32 v114, v118
	v_mfma_f32_16x16x32_bf16 v[80:83], v[108:111], v[64:67], v[80:83]
	v_exp_f32_e32 v115, v119
	s_waitcnt lgkmcnt(2)
	v_mfma_f32_16x16x32_bf16 v[84:87], v[104:107], v[52:55], v[84:87]
	v_cvt_pk_bf16_f32 v68, v68, v69
	v_cvt_pk_bf16_f32 v69, v70, v71
	v_cvt_pk_bf16_f32 v70, v112, v113
	v_mfma_f32_16x16x32_bf16 v[72:75], v[104:107], v[64:67], v[72:75]
	v_cvt_pk_bf16_f32 v71, v114, v115
	v_exp_f32_e32 v108, v124
	v_exp_f32_e32 v109, v125
	v_exp_f32_e32 v110, v126
	v_exp_f32_e32 v111, v127
	s_waitcnt lgkmcnt(0)
	v_mfma_f32_16x16x32_bf16 v[40:43], v[100:103], v[52:55], v[40:43]
	v_exp_f32_e32 v104, v128
	v_exp_f32_e32 v105, v129
	v_exp_f32_e32 v106, v130
	v_mfma_f32_16x16x32_bf16 v[44:47], v[100:103], v[64:67], v[44:47]
	v_exp_f32_e32 v107, v131
	v_mfma_f32_16x16x32_bf16 v[76:79], v[132:135], v[52:55], v[76:79]
	v_mfma_f32_16x16x32_bf16 v[60:63], v[132:135], v[64:67], v[60:63]
	s_waitcnt lgkmcnt(0)
	s_barrier
	v_cvt_pk_bf16_f32 v52, v140, v141
	v_cvt_pk_bf16_f32 v53, v142, v143
	v_cvt_pk_bf16_f32 v54, v144, v145
	v_cvt_pk_bf16_f32 v55, v146, v147
	v_cvt_pk_bf16_f32 v64, v108, v109
	v_cvt_pk_bf16_f32 v65, v110, v111
	v_cvt_pk_bf16_f32 v66, v104, v105
	v_cvt_pk_bf16_f32 v67, v106, v107
	s_cmp_lg_u32 s82, s10
	s_cbranch_scc0 .LBB0_156
	s_mov_b32 s1, s10
	s_branch .LBB0_190
